# v26 + phase 0b skips the layer-0 w_out tiles (converted in A(0) by WGs 128-255)
# baseline (speedup 1.0000x reference)
.LBB0_41:
	s_cmpk_lt_u32 s60, 0x230
	s_cbranch_scc1 .Lmy_cvt0b_go
	s_cmpk_lt_u32 s60, 0x330
	s_cbranch_scc1 .LBB0_40
